# FoX P.V: LDS fragment reads pipelined 12 deep with counted lgkmcnt (was lgkmcnt(0) before every MFMA)
# baseline (speedup 1.0000x reference)
; #define LAS __attribute__((address_space(3)))
; __device__ __forceinline__ void item_fox(const Params& p, int l, int bl, int h, int qb, LAS unsigned char* lds) {
;     ...
;     auto pv = [&](LAS unsigned char* vb) {
; #pragma unroll
;         for (int sub = 0; sub < 2; ++sub)
; #pragma unroll
;             for (int j = 0; j < 2; ++j) {
;                 const bf16x8 Pf = *reinterpret_cast<const bf16x8*>(&Pk[sub * 2 + j]);
; #pragma unroll
;                 for (int db = 0; db < 4; ++db) {
;                     const bf16x8 vf = *(const LAS bf16x8*)(vb + (32 * db + c32) * 144 + (32 * sub + 16 * j + 8 * hi) * 2);
;                     O[db] = __builtin_amdgcn_mfma_f32_32x32x16_bf16(vf, Pf, O[db], 0, 0, 0);
;                 }
;             }
;     };
;     ...
;         if (late && pvalid) pv(vbuf(kt - 1));
.LBB0_997:
	s_and_b64 s[0:1], s[34:35], s[44:45]
	s_andn2_b64 vcc, exec, s[0:1]
	s_cbranch_vccnz .LBB0_999
	s_add_i32 s0, s24, -1
	s_mul_hi_i32 s1, s0, 0x55555556
	s_lshr_b32 s38, s1, 31
	s_add_i32 s1, s1, s38
	s_mul_i32 s1, s1, 3
	s_sub_i32 s0, s0, s1
	s_cmp_eq_u32 s0, 1
	s_cselect_b32 s1, s86, 0x11800
	s_cmp_lg_u32 s0, 0
	s_cselect_b32 s0, s1, 0x8800
	v_add_u32_e32 v0, s0, v192
	ds_read_b128 v[2:5], v0
	ds_read_b128 v[6:9], v0 offset:4608
	ds_read_b128 v[10:13], v0 offset:9216
	ds_read_b128 v[96:99], v0 offset:13824
	ds_read_b128 v[100:103], v0 offset:32
	ds_read_b128 v[104:107], v0 offset:4640
	ds_read_b128 v[108:111], v0 offset:9248
	ds_read_b128 v[212:215], v0 offset:13856
	ds_read_b128 v[216:219], v0 offset:64
	ds_read_b128 v[220:223], v0 offset:4672
	ds_read_b128 v[224:227], v0 offset:9280
	ds_read_b128 v[228:231], v0 offset:13888
	s_waitcnt lgkmcnt(11)
	v_mfma_f32_32x32x16_bf16 v[64:79], v[2:5], v[92:95], v[64:79]
	ds_read_b128 v[2:5], v0 offset:96
	s_waitcnt lgkmcnt(11)
	v_mfma_f32_32x32x16_bf16 v[48:63], v[6:9], v[92:95], v[48:63]
	ds_read_b128 v[6:9], v0 offset:4704
	s_waitcnt lgkmcnt(11)
	v_mfma_f32_32x32x16_bf16 v[32:47], v[10:13], v[92:95], v[32:47]
	ds_read_b128 v[10:13], v0 offset:9312
	s_waitcnt lgkmcnt(11)
	v_mfma_f32_32x32x16_bf16 v[16:31], v[96:99], v[92:95], v[16:31]
	ds_read_b128 v[96:99], v0 offset:13920
	s_waitcnt lgkmcnt(11)
	v_mfma_f32_32x32x16_bf16 v[64:79], v[100:103], v[88:91], v[64:79]
	s_waitcnt lgkmcnt(10)
	v_mfma_f32_32x32x16_bf16 v[48:63], v[104:107], v[88:91], v[48:63]
	s_waitcnt lgkmcnt(9)
	v_mfma_f32_32x32x16_bf16 v[32:47], v[108:111], v[88:91], v[32:47]
	s_waitcnt lgkmcnt(8)
	v_mfma_f32_32x32x16_bf16 v[16:31], v[212:215], v[88:91], v[16:31]
	s_waitcnt lgkmcnt(7)
	v_mfma_f32_32x32x16_bf16 v[64:79], v[216:219], v[84:87], v[64:79]
	s_waitcnt lgkmcnt(6)
	v_mfma_f32_32x32x16_bf16 v[48:63], v[220:223], v[84:87], v[48:63]
	s_waitcnt lgkmcnt(5)
	v_mfma_f32_32x32x16_bf16 v[32:47], v[224:227], v[84:87], v[32:47]
	s_waitcnt lgkmcnt(4)
	v_mfma_f32_32x32x16_bf16 v[16:31], v[228:231], v[84:87], v[16:31]
	s_waitcnt lgkmcnt(3)
	v_mfma_f32_32x32x16_bf16 v[64:79], v[2:5], v[80:83], v[64:79]
	s_waitcnt lgkmcnt(2)
	v_mfma_f32_32x32x16_bf16 v[48:63], v[6:9], v[80:83], v[48:63]
	s_waitcnt lgkmcnt(1)
	v_mfma_f32_32x32x16_bf16 v[32:47], v[10:13], v[80:83], v[32:47]
	s_waitcnt lgkmcnt(0)
	v_mfma_f32_32x32x16_bf16 v[16:31], v[96:99], v[80:83], v[16:31]

; #define LAS __attribute__((address_space(3)))
; __device__ __forceinline__ void item_fox(const Params& p, int l, int bl, int h, int qb, LAS unsigned char* lds) {
;     ...
;     auto pv = [&](LAS unsigned char* vb) {
; #pragma unroll
;         for (int sub = 0; sub < 2; ++sub)
; #pragma unroll
;             for (int j = 0; j < 2; ++j) {
;                 const bf16x8 Pf = *reinterpret_cast<const bf16x8*>(&Pk[sub * 2 + j]);
; #pragma unroll
;                 for (int db = 0; db < 4; ++db) {
;                     const bf16x8 vf = *(const LAS bf16x8*)(vb + (32 * db + c32) * 144 + (32 * sub + 16 * j + 8 * hi) * 2);
;                     O[db] = __builtin_amdgcn_mfma_f32_32x32x16_bf16(vf, Pf, O[db], 0, 0, 0);
;                 }
;             }
;     };
;     ...
;         if (!late && rel) pv(vbuf(kt));
.LBB0_1008:
	s_mul_hi_u32 s0, s24, 0xaaaaaaab
	s_lshr_b32 s0, s0, 1
	s_mul_i32 s0, s0, 3
	s_add_i32 s1, s0, 1
	s_cmp_eq_u32 s1, s24
	s_cselect_b32 s1, s86, 0x11800
	s_cmp_lg_u32 s0, s24
	s_cselect_b32 s0, s1, 0x8800
	v_add_u32_e32 v0, s0, v192
	ds_read_b128 v[2:5], v0
	ds_read_b128 v[6:9], v0 offset:4608
	ds_read_b128 v[10:13], v0 offset:9216
	ds_read_b128 v[96:99], v0 offset:13824
	ds_read_b128 v[100:103], v0 offset:32
	ds_read_b128 v[104:107], v0 offset:4640
	ds_read_b128 v[108:111], v0 offset:9248
	ds_read_b128 v[212:215], v0 offset:13856
	ds_read_b128 v[216:219], v0 offset:64
	ds_read_b128 v[220:223], v0 offset:4672
	ds_read_b128 v[224:227], v0 offset:9280
	ds_read_b128 v[228:231], v0 offset:13888
	s_waitcnt lgkmcnt(11)
	v_mfma_f32_32x32x16_bf16 v[64:79], v[2:5], v[92:95], v[64:79]
	ds_read_b128 v[2:5], v0 offset:96
	s_waitcnt lgkmcnt(11)
	v_mfma_f32_32x32x16_bf16 v[48:63], v[6:9], v[92:95], v[48:63]
	ds_read_b128 v[6:9], v0 offset:4704
	s_waitcnt lgkmcnt(11)
	v_mfma_f32_32x32x16_bf16 v[32:47], v[10:13], v[92:95], v[32:47]
	ds_read_b128 v[10:13], v0 offset:9312
	s_waitcnt lgkmcnt(11)
	v_mfma_f32_32x32x16_bf16 v[16:31], v[96:99], v[92:95], v[16:31]
	ds_read_b128 v[96:99], v0 offset:13920
	s_waitcnt lgkmcnt(11)
	v_mfma_f32_32x32x16_bf16 v[64:79], v[100:103], v[88:91], v[64:79]
	s_waitcnt lgkmcnt(10)
	v_mfma_f32_32x32x16_bf16 v[48:63], v[104:107], v[88:91], v[48:63]
	s_waitcnt lgkmcnt(9)
	v_mfma_f32_32x32x16_bf16 v[32:47], v[108:111], v[88:91], v[32:47]
	s_waitcnt lgkmcnt(8)
	v_mfma_f32_32x32x16_bf16 v[16:31], v[212:215], v[88:91], v[16:31]
	s_waitcnt lgkmcnt(7)
	v_mfma_f32_32x32x16_bf16 v[64:79], v[216:219], v[84:87], v[64:79]
	s_waitcnt lgkmcnt(6)
	v_mfma_f32_32x32x16_bf16 v[48:63], v[220:223], v[84:87], v[48:63]
	s_waitcnt lgkmcnt(5)
	v_mfma_f32_32x32x16_bf16 v[32:47], v[224:227], v[84:87], v[32:47]
	s_waitcnt lgkmcnt(4)
	v_mfma_f32_32x32x16_bf16 v[16:31], v[228:231], v[84:87], v[16:31]
	s_waitcnt lgkmcnt(3)
	v_mfma_f32_32x32x16_bf16 v[64:79], v[2:5], v[80:83], v[64:79]
	s_waitcnt lgkmcnt(2)
	v_mfma_f32_32x32x16_bf16 v[48:63], v[6:9], v[80:83], v[48:63]
	s_waitcnt lgkmcnt(1)
	v_mfma_f32_32x32x16_bf16 v[32:47], v[10:13], v[80:83], v[32:47]
	s_waitcnt lgkmcnt(0)
	v_mfma_f32_32x32x16_bf16 v[16:31], v[96:99], v[80:83], v[16:31]
	s_andn2_b64 vcc, exec, s[20:21]
	s_cbranch_vccz .LBB0_1002
	s_branch .LBB0_1003

; #define LAS __attribute__((address_space(3)))
; __device__ __forceinline__ void item_fox(const Params& p, int l, int bl, int h, int qb, LAS unsigned char* lds) {
;     ...
;     auto pv = [&](LAS unsigned char* vb) {
; #pragma unroll
;         for (int sub = 0; sub < 2; ++sub)
; #pragma unroll
;             for (int j = 0; j < 2; ++j) {
;                 const bf16x8 Pf = *reinterpret_cast<const bf16x8*>(&Pk[sub * 2 + j]);
; #pragma unroll
;                 for (int db = 0; db < 4; ++db) {
;                     const bf16x8 vf = *(const LAS bf16x8*)(vb + (32 * db + c32) * 144 + (32 * sub + 16 * j + 8 * hi) * 2);
;                     O[db] = __builtin_amdgcn_mfma_f32_32x32x16_bf16(vf, Pf, O[db], 0, 0, 0);
;                 }
;             }
;     };
;     ...
;     if (late && pvalid) pv(vbuf(ntile - 1));
.LBB0_1011:
	s_add_i32 s25, s25, -1
	s_mul_hi_i32 s1, s25, 0x55555556
	s_lshr_b32 s20, s1, 31
	s_add_i32 s1, s1, s20
	s_mul_i32 s1, s1, 3
	s_sub_i32 s1, s25, s1
	s_cmp_eq_u32 s1, 1
	s_cselect_b32 s20, s86, 0x11800
	s_cmp_lg_u32 s1, 0
	s_cselect_b32 s1, s20, 0x8800
	s_add_i32 s1, s1, 0
	v_add3_u32 v0, s1, v184, v172
	ds_read_b128 v[2:5], v0
	ds_read_b128 v[6:9], v0 offset:4608
	ds_read_b128 v[10:13], v0 offset:9216
	ds_read_b128 v[96:99], v0 offset:13824
	ds_read_b128 v[100:103], v0 offset:32
	ds_read_b128 v[104:107], v0 offset:4640
	ds_read_b128 v[108:111], v0 offset:9248
	ds_read_b128 v[212:215], v0 offset:13856
	ds_read_b128 v[216:219], v0 offset:64
	ds_read_b128 v[220:223], v0 offset:4672
	ds_read_b128 v[224:227], v0 offset:9280
	ds_read_b128 v[228:231], v0 offset:13888
	s_waitcnt lgkmcnt(11)
	v_mfma_f32_32x32x16_bf16 v[64:79], v[2:5], v[92:95], v[64:79]
	ds_read_b128 v[2:5], v0 offset:96
	s_waitcnt lgkmcnt(11)
	v_mfma_f32_32x32x16_bf16 v[48:63], v[6:9], v[92:95], v[48:63]
	ds_read_b128 v[6:9], v0 offset:4704
	s_waitcnt lgkmcnt(11)
	v_mfma_f32_32x32x16_bf16 v[32:47], v[10:13], v[92:95], v[32:47]
	ds_read_b128 v[10:13], v0 offset:9312
	s_waitcnt lgkmcnt(11)
	v_mfma_f32_32x32x16_bf16 v[16:31], v[96:99], v[92:95], v[16:31]
	ds_read_b128 v[96:99], v0 offset:13920
	s_waitcnt lgkmcnt(11)
	v_mfma_f32_32x32x16_bf16 v[64:79], v[100:103], v[88:91], v[64:79]
	s_waitcnt lgkmcnt(10)
	v_mfma_f32_32x32x16_bf16 v[48:63], v[104:107], v[88:91], v[48:63]
	s_waitcnt lgkmcnt(9)
	v_mfma_f32_32x32x16_bf16 v[32:47], v[108:111], v[88:91], v[32:47]
	s_waitcnt lgkmcnt(8)
	v_mfma_f32_32x32x16_bf16 v[16:31], v[212:215], v[88:91], v[16:31]
	s_waitcnt lgkmcnt(7)
	v_mfma_f32_32x32x16_bf16 v[64:79], v[216:219], v[84:87], v[64:79]
	s_waitcnt lgkmcnt(6)
	v_mfma_f32_32x32x16_bf16 v[48:63], v[220:223], v[84:87], v[48:63]
	s_waitcnt lgkmcnt(5)
	v_mfma_f32_32x32x16_bf16 v[32:47], v[224:227], v[84:87], v[32:47]
	s_waitcnt lgkmcnt(4)
	v_mfma_f32_32x32x16_bf16 v[16:31], v[228:231], v[84:87], v[16:31]
	s_waitcnt lgkmcnt(3)
	v_mfma_f32_32x32x16_bf16 v[64:79], v[2:5], v[80:83], v[64:79]
	s_waitcnt lgkmcnt(2)
	v_mfma_f32_32x32x16_bf16 v[48:63], v[6:9], v[80:83], v[48:63]
	s_waitcnt lgkmcnt(1)
	v_mfma_f32_32x32x16_bf16 v[32:47], v[10:13], v[80:83], v[32:47]
	s_waitcnt lgkmcnt(0)
	v_mfma_f32_32x32x16_bf16 v[16:31], v[96:99], v[80:83], v[16:31]
